# P7 unit start: accumulators zeroed with 64 v_mov_b64 instead of 128 v_mov_b32
# speedup vs baseline: 1.0012x; 1.0012x over previous
; #define PG8_BAR __builtin_amdgcn_s_barrier()
; template <class Epi, class Sched, bool ALIGN_EPI = true, bool SP2 = true, class Pre = NoPre>
; __device__ __forceinline__ void gemm_phase(LAS unsigned char* lds, const Gemm g, const Sched& S, const Epi& E, const Pre& pre = Pre()) {
;     ...
;         const bool has_next = S.next(ui + 1, nxt);
;         const char* nA = has_next ? PG8_TILE_A(nxt) : cA; const char* nB = has_next ? PG8_TILE_B(nxt) : cB;
;         for (int t = 0; t < nt; t += 2) {
;             S.k_hook(t, wid);
;             const bool last = (t == nt - 2);
;             const char* a1 = cA + (size_t)(t + 1) * kstep;
;             const char* a2 = last ? nA : cA + (size_t)(t + 2) * kstep; const char* b2 = last ? nB : cB + (size_t)(t + 2) * kstep;
;             const char* a3 = a2 + kstep; const char* b3 = b2 + kstep;
;             if constexpr (SP2) {
;             PG8_LDB(B0, 0, 0); PG8_LDB(B1, 0, 1); PG8_SCHED; PG8_LDA(At, 0, 0); PG8_STAGE(PG8_SA(1, 1), a1 + hsA, voffA);
;             PG8_WAIT_V(8); PG8_WAIT_L(0); PG8_BAR; PG8_MMA(0, 0, At, B0); PG8_MMA(0, 1, At, B1); PG8_BAR; PG8_SCHED;
;             PG8_LDA(At, 0, 1); PG8_STAGE(PG8_SB(0, 0), b2, voffB); PG8_STAGE(PG8_SB(0, 1), b2 + hsB, voffB); PG8_STAGE(PG8_SA(0, 0), a2, voffA);
;             PG8_WAIT_V(8); PG8_WAIT_L(0); PG8_BAR; PG8_MMA(1, 0, At, B0); PG8_MMA(1, 1, At, B1); PG8_BAR; PG8_SCHED;
;             PG8_LDB(B0, 1, 0); PG8_LDB(B1, 1, 1); PG8_SCHED; PG8_LDA(At, 1, 0); PG8_STAGE(PG8_SA(0, 1), a2 + hsA, voffA);
;             PG8_WAIT_V(8); PG8_WAIT_L(0); PG8_BAR; PG8_MMA(0, 0, At, B0); PG8_MMA(0, 1, At, B1); PG8_BAR; PG8_SCHED;
;             PG8_LDA(At, 1, 1); PG8_STAGE(PG8_SB(1, 0), b3, voffB); PG8_STAGE(PG8_SB(1, 1), b3 + hsB, voffB); PG8_STAGE(PG8_SA(1, 0), a3, voffA);
;             PG8_WAIT_V(8); PG8_WAIT_L(0); PG8_BAR; PG8_MMA(1, 0, At, B0); PG8_MMA(1, 1, At, B1); PG8_BAR; PG8_SCHED;
;             } else {
;             PG8_LDB(B0, 0, 0); PG8_SCHED; PG8_LDA(At, 0, 0); PG8_STAGE(PG8_SA(1, 1), a1 + hsA, voffA);
;             PG8_WAIT_L(8); PG8_BAR; PG8_WAIT_L(0); PG8_MMA(0, 0, At, B0); PG8_BAR; PG8_SCHED;
;             PG8_LDB(B1, 0, 1); PG8_STAGE(PG8_SB(0, 0), b2, voffB);
;             PG8_BAR; PG8_WAIT_L(0); PG8_MMA(0, 1, At, B1); PG8_BAR;
;             PG8_LDA(At, 0, 1); PG8_STAGE(PG8_SA(0, 0), a2, voffA);
;             PG8_BAR; PG8_WAIT_L(0); PG8_MMA(1, 0, At, B0); PG8_BAR; PG8_SCHED;
.LBB0_857:
	s_ashr_i32 s21, s20, 31
	s_lshl_b64 s[10:11], s[20:21], 19
	s_add_u32 s22, s54, s10
	s_addc_u32 s23, s55, s11
	s_and_b64 s[10:11], s[40:41], exec
	s_cselect_b32 s21, s23, s39
	s_cselect_b32 s45, s22, s38
	s_ashr_i32 s17, s16, 31
	s_lshl_b64 s[10:11], s[16:17], 19
	v_readlane_b32 s80, v254, 55
	s_add_u32 s24, s80, s10
	s_addc_u32 s25, s3, s11
	s_and_b64 s[10:11], s[40:41], exec
	s_cselect_b32 s17, s25, s31
	s_cselect_b32 s46, s24, s30
	s_add_u32 s47, s30, 0x100
	s_addc_u32 s53, s31, 0
	s_add_u32 s30, s38, 0x40080
	v_mov_b64_e32 v[0:1], 0
	v_mov_b64_e32 v[2:3], 0
	v_mov_b64_e32 v[4:5], 0
	v_mov_b64_e32 v[6:7], 0
	v_mov_b64_e32 v[8:9], 0
	v_mov_b64_e32 v[10:11], 0
	v_mov_b64_e32 v[12:13], 0
	v_mov_b64_e32 v[14:15], 0
	v_mov_b64_e32 v[16:17], 0
	v_mov_b64_e32 v[18:19], 0
	v_mov_b64_e32 v[20:21], 0
	v_mov_b64_e32 v[22:23], 0
	v_mov_b64_e32 v[24:25], 0
	v_mov_b64_e32 v[26:27], 0
	v_mov_b64_e32 v[28:29], 0
	v_mov_b64_e32 v[30:31], 0
	v_mov_b64_e32 v[32:33], 0
	v_mov_b64_e32 v[34:35], 0
	v_mov_b64_e32 v[36:37], 0
	v_mov_b64_e32 v[38:39], 0
	v_mov_b64_e32 v[40:41], 0
	v_mov_b64_e32 v[42:43], 0
	v_mov_b64_e32 v[44:45], 0
	v_mov_b64_e32 v[46:47], 0
	v_mov_b64_e32 v[48:49], 0
	v_mov_b64_e32 v[50:51], 0
	v_mov_b64_e32 v[52:53], 0
	v_mov_b64_e32 v[54:55], 0
	v_mov_b64_e32 v[56:57], 0
	v_mov_b64_e32 v[58:59], 0
	v_mov_b64_e32 v[60:61], 0
	v_mov_b64_e32 v[62:63], 0
	v_mov_b64_e32 v[64:65], 0
	v_mov_b64_e32 v[66:67], 0
	v_mov_b64_e32 v[68:69], 0
	v_mov_b64_e32 v[70:71], 0
	v_mov_b64_e32 v[72:73], 0
	v_mov_b64_e32 v[74:75], 0
	v_mov_b64_e32 v[76:77], 0
	v_mov_b64_e32 v[78:79], 0
	v_mov_b64_e32 v[80:81], 0
	v_mov_b64_e32 v[82:83], 0
	v_mov_b64_e32 v[84:85], 0
	v_mov_b64_e32 v[86:87], 0
	v_mov_b64_e32 v[88:89], 0
	v_mov_b64_e32 v[90:91], 0
	v_mov_b64_e32 v[92:93], 0
	v_mov_b64_e32 v[94:95], 0
	v_mov_b64_e32 v[96:97], 0
	v_mov_b64_e32 v[98:99], 0
	v_mov_b64_e32 v[100:101], 0
	v_mov_b64_e32 v[102:103], 0
	v_mov_b64_e32 v[104:105], 0
	v_mov_b64_e32 v[106:107], 0
	v_mov_b64_e32 v[108:109], 0
	v_mov_b64_e32 v[110:111], 0
	v_mov_b64_e32 v[112:113], 0
	v_mov_b64_e32 v[114:115], 0
	v_mov_b64_e32 v[116:117], 0
	v_mov_b64_e32 v[118:119], 0
	v_mov_b64_e32 v[120:121], 0
	v_mov_b64_e32 v[122:123], 0
	v_mov_b64_e32 v[124:125], 0
	v_mov_b64_e32 v[126:127], 0
	s_addc_u32 s31, s39, 0
	s_mov_b32 s58, -2
	v_readlane_b32 s81, v254, 56
	v_readlane_b32 s82, v254, 57
	v_readlane_b32 s83, v254, 58
